# GEMM LDS-DMA loads use the SGPR-base address form (44 sites, no 64-bit VALU address add) on top of the packed accumulator clear
# baseline (speedup 1.0000x reference)
; #define PG8_STAGE(bufoff, gbase, voff) do { _Pragma("unroll") for (int _i = 0; _i < 2; ++_i) \
;         __builtin_amdgcn_global_load_lds((const unsigned*)((const char*)(gbase) + (voff)[_i]), (PG8_LAS unsigned*)(lds + (bufoff) + ldsw + _i * 8192), 16, 0, 0); } while (0)
; #define PG8_LDA(dst, b, h) do { _Pragma("unroll") for (int m = 0; m < 4; ++m) _Pragma("unroll") for (int k = 0; k < 2; ++k) dst[m][k] = *(const PG8_LAS bf16x8*)(lds + PG8_SA(b, h) + aoff + m * 2048 + k * 1024); } while (0)
; #define PG8_LDB(dst, b, h) do { _Pragma("unroll") for (int n = 0; n < 2; ++n) _Pragma("unroll") for (int k = 0; k < 2; ++k) dst[n][k] = *(const PG8_LAS bf16x8*)(lds + PG8_SB(b, h) + boff + n * 2048 + k * 1024); } while (0)
; #define PG8_MMA(ai, bj, At, Bt) do { __builtin_amdgcn_s_setprio(1); _Pragma("unroll") for (int m = 0; m < 4; ++m) _Pragma("unroll") for (int n = 0; n < 2; ++n) _Pragma("unroll") for (int k = 0; k < 2; ++k) \
;         acc[ai][bj][m][n] = __builtin_amdgcn_mfma_f32_16x16x32_bf16(Bt[n][k], At[m][k], acc[ai][bj][m][n], 0, 0, 0); __builtin_amdgcn_s_setprio(0); } while (0)
; #define PG8_WAIT_V(n) asm volatile("s_waitcnt vmcnt(" #n ")" ::: "memory")
; #define PG8_WAIT_L(n) asm volatile("s_waitcnt lgkmcnt(" #n ")" ::: "memory")
; #define PG8_BAR __builtin_amdgcn_s_barrier()
; #define PG8_SCHED __builtin_amdgcn_sched_barrier(0)
; template <class Epi, class Sched, bool ALIGN_EPI = false, bool SP2 = false>
; __device__ __forceinline__ void gemm_phase(PG8_LAS unsigned char* lds, const Gemm g, const Sched& S, const Epi& E, int wv) {
;     ...
;             PG8_LDB(B0, 0, 0); PG8_LDB(B1, 0, 1); PG8_SCHED; PG8_LDA(At, 0, 0); PG8_STAGE(PG8_SA(1, 1), a1 + hstepA, voffA);
;             PG8_WAIT_V(8); PG8_WAIT_L(0); PG8_BAR; PG8_MMA(0, 0, At, B0); PG8_MMA(0, 1, At, B1); PG8_BAR; PG8_SCHED;
;             PG8_LDA(At, 0, 1); PG8_STAGE(PG8_SB(0, 0), b2, voffB); PG8_STAGE(PG8_SB(0, 1), b2 + hstepB, voffB); PG8_STAGE(PG8_SA(0, 0), a2, voffA);
;             PG8_WAIT_V(8); PG8_WAIT_L(0); PG8_BAR; PG8_MMA(1, 0, At, B0); PG8_MMA(1, 1, At, B1); PG8_BAR; PG8_SCHED;
.LBB0_1893:
	s_add_u32 s2, s40, 0xfffc0080
	s_addc_u32 s3, s41, -1
	s_add_i32 s60, 0, 0x10000
	s_cmp_eq_u32 s96, 12
	s_cselect_b32 s43, s39, s3
	s_cselect_b32 s42, s92, s2
	s_cselect_b32 s3, s37, s95
	s_cselect_b32 s2, s93, s94
	s_add_i32 s61, 0, 0x14000
	v_add_u32_e32 v46, s60, v180
	v_add_u32_e32 v62, s61, v180
	ds_read_b128 v[34:37], v46
	ds_read_b128 v[38:41], v46 offset:1024
	ds_read_b128 v[42:45], v46 offset:2048
	ds_read_b128 v[46:49], v46 offset:3072
	ds_read_b128 v[50:53], v62
	ds_read_b128 v[54:57], v62 offset:1024
	ds_read_b128 v[58:61], v62 offset:2048
	ds_read_b128 v[62:65], v62 offset:3072
	s_add_i32 m0, s35, 0xc000
	ds_read_b128 v[172:175], v181
	ds_read_b128 v[182:185], v181 offset:1024
	ds_read_b128 v[220:223], v181 offset:2048
	ds_read_b128 v[224:227], v181 offset:3072
	ds_read_b128 v[228:231], v181 offset:4096
	ds_read_b128 v[242:245], v181 offset:5120
	ds_read_b128 v[246:249], v181 offset:6144
	ds_read_b128 v[250:253], v181 offset:7168
	global_load_lds_dwordx4 v168, s[40:41]
	s_add_i32 m0, s35, 0xe000
	s_nop 0
	global_load_lds_dwordx4 v170, s[40:41]
	s_waitcnt vmcnt(8)
	s_waitcnt lgkmcnt(0)
	s_barrier
	s_setprio 1
	s_waitcnt lgkmcnt(0)
	v_mfma_f32_16x16x32_bf16 v[158:161], v[34:37], v[172:175], v[158:161]
	v_mfma_f32_16x16x32_bf16 v[154:157], v[42:45], v[172:175], v[154:157]
	v_mfma_f32_16x16x32_bf16 v[142:145], v[34:37], v[220:223], v[142:145]
	v_mfma_f32_16x16x32_bf16 v[138:141], v[42:45], v[220:223], v[138:141]
	v_mfma_f32_16x16x32_bf16 v[126:129], v[34:37], v[228:231], v[126:129]
	v_mfma_f32_16x16x32_bf16 v[122:125], v[42:45], v[228:231], v[122:125]
	v_mfma_f32_16x16x32_bf16 v[110:113], v[34:37], v[246:249], v[110:113]
	v_mfma_f32_16x16x32_bf16 v[106:109], v[42:45], v[246:249], v[106:109]
	v_mfma_f32_16x16x32_bf16 v[158:161], v[38:41], v[182:185], v[158:161]
	v_mfma_f32_16x16x32_bf16 v[154:157], v[46:49], v[182:185], v[154:157]
	v_mfma_f32_16x16x32_bf16 v[142:145], v[38:41], v[224:227], v[142:145]
	v_mfma_f32_16x16x32_bf16 v[138:141], v[46:49], v[224:227], v[138:141]
	v_mfma_f32_16x16x32_bf16 v[126:129], v[38:41], v[242:245], v[126:129]
	v_mfma_f32_16x16x32_bf16 v[122:125], v[46:49], v[242:245], v[122:125]
	v_mfma_f32_16x16x32_bf16 v[110:113], v[38:41], v[250:253], v[110:113]
	v_mfma_f32_16x16x32_bf16 v[106:109], v[46:49], v[250:253], v[106:109]
	s_setprio 0
	s_setprio 1
	v_mfma_f32_16x16x32_bf16 v[150:153], v[50:53], v[172:175], v[150:153]
	v_mfma_f32_16x16x32_bf16 v[146:149], v[58:61], v[172:175], v[146:149]
	v_mfma_f32_16x16x32_bf16 v[134:137], v[50:53], v[220:223], v[134:137]
	v_mfma_f32_16x16x32_bf16 v[130:133], v[58:61], v[220:223], v[130:133]
	v_mfma_f32_16x16x32_bf16 v[118:121], v[50:53], v[228:231], v[118:121]
	v_mfma_f32_16x16x32_bf16 v[114:117], v[58:61], v[228:231], v[114:117]
	v_mfma_f32_16x16x32_bf16 v[102:105], v[50:53], v[246:249], v[102:105]
	v_mfma_f32_16x16x32_bf16 v[98:101], v[58:61], v[246:249], v[98:101]
	v_mfma_f32_16x16x32_bf16 v[150:153], v[54:57], v[182:185], v[150:153]
	v_mfma_f32_16x16x32_bf16 v[146:149], v[62:65], v[182:185], v[146:149]
	v_mfma_f32_16x16x32_bf16 v[134:137], v[54:57], v[224:227], v[134:137]
	v_mfma_f32_16x16x32_bf16 v[130:133], v[62:65], v[224:227], v[130:133]
	v_mfma_f32_16x16x32_bf16 v[118:121], v[54:57], v[242:245], v[118:121]
	v_mfma_f32_16x16x32_bf16 v[114:117], v[62:65], v[242:245], v[114:117]
	v_mfma_f32_16x16x32_bf16 v[102:105], v[54:57], v[250:253], v[102:105]
	v_mfma_f32_16x16x32_bf16 v[98:101], v[62:65], v[250:253], v[98:101]
	s_setprio 0
	s_barrier
	s_add_i32 s60, s60, s50
	v_lshl_add_u64 v[176:177], s[2:3], 0, v[0:1]
	s_mov_b32 m0, s60
	ds_read_b128 v[172:175], v181 offset:16384
	ds_read_b128 v[182:185], v181 offset:17408
	ds_read_b128 v[220:223], v181 offset:18432
	ds_read_b128 v[224:227], v181 offset:19456
	ds_read_b128 v[228:231], v181 offset:20480
	ds_read_b128 v[242:245], v181 offset:21504
	ds_read_b128 v[246:249], v181 offset:22528
	ds_read_b128 v[250:253], v181 offset:23552
	global_load_lds_dwordx4 v[176:177], off
	s_add_i32 m0, s60, 0x2000
	s_add_u32 vcc_lo, s2, 0x40000
	v_lshl_add_u64 v[186:187], s[2:3], 0, v[162:163]
	s_addc_u32 vcc_hi, s3, 0
	s_add_i32 s60, s61, s50
	global_load_lds_dwordx4 v[186:187], off
	v_lshl_add_u64 v[196:197], vcc, 0, v[0:1]
	s_mov_b32 m0, s60
	v_lshl_add_u64 v[240:241], s[42:43], 0, v[164:165]
	global_load_lds_dwordx4 v[196:197], off
	v_lshl_add_u64 v[196:197], vcc, 0, v[162:163]
	s_add_i32 m0, s60, 0x2000
	s_nop 0
	global_load_lds_dwordx4 v[196:197], off
	v_lshl_add_u64 v[196:197], s[42:43], 0, v[166:167]
	s_mov_b32 m0, s35
	s_nop 0
	global_load_lds_dwordx4 v[196:197], off
	s_mov_b32 m0, s52
	s_nop 0
	global_load_lds_dwordx4 v[240:241], off
	s_waitcnt vmcnt(8)
	s_waitcnt lgkmcnt(0)
	s_barrier
; #define PG8_STAGE(bufoff, gbase, voff) do { _Pragma("unroll") for (int _i = 0; _i < 2; ++_i) \
;         __builtin_amdgcn_global_load_lds((const unsigned*)((const char*)(gbase) + (voff)[_i]), (PG8_LAS unsigned*)(lds + (bufoff) + ldsw + _i * 8192), 16, 0, 0); } while (0)
; #define PG8_LDA(dst, b, h) do { _Pragma("unroll") for (int m = 0; m < 4; ++m) _Pragma("unroll") for (int k = 0; k < 2; ++k) dst[m][k] = *(const PG8_LAS bf16x8*)(lds + PG8_SA(b, h) + aoff + m * 2048 + k * 1024); } while (0)
; #define PG8_LDB(dst, b, h) do { _Pragma("unroll") for (int n = 0; n < 2; ++n) _Pragma("unroll") for (int k = 0; k < 2; ++k) dst[n][k] = *(const PG8_LAS bf16x8*)(lds + PG8_SB(b, h) + boff + n * 2048 + k * 1024); } while (0)
; #define PG8_MMA(ai, bj, At, Bt) do { __builtin_amdgcn_s_setprio(1); _Pragma("unroll") for (int m = 0; m < 4; ++m) _Pragma("unroll") for (int n = 0; n < 2; ++n) _Pragma("unroll") for (int k = 0; k < 2; ++k) \
;         acc[ai][bj][m][n] = __builtin_amdgcn_mfma_f32_16x16x32_bf16(Bt[n][k], At[m][k], acc[ai][bj][m][n], 0, 0, 0); __builtin_amdgcn_s_setprio(0); } while (0)
; #define PG8_WAIT_V(n) asm volatile("s_waitcnt vmcnt(" #n ")" ::: "memory")
; #define PG8_WAIT_L(n) asm volatile("s_waitcnt lgkmcnt(" #n ")" ::: "memory")
; #define PG8_BAR __builtin_amdgcn_s_barrier()
; #define PG8_SCHED __builtin_amdgcn_sched_barrier(0)
; template <class Epi, class Sched, bool ALIGN_EPI = false, bool SP2 = false>
; __device__ __forceinline__ void gemm_phase(PG8_LAS unsigned char* lds, const Gemm g, const Sched& S, const Epi& E, int wv) {
;     ...
;             PG8_WAIT_V(8); PG8_WAIT_L(0); PG8_BAR; PG8_MMA(1, 0, At, B0); PG8_MMA(1, 1, At, B1); PG8_BAR; PG8_SCHED;
;             PG8_LDB(B0, 1, 0); PG8_LDB(B1, 1, 1); PG8_SCHED; PG8_LDA(At, 1, 0); PG8_STAGE(PG8_SA(0, 1), a2 + hstepA, voffA);
;             PG8_WAIT_V(8); PG8_WAIT_L(0); PG8_BAR; PG8_MMA(0, 0, At, B0); PG8_MMA(0, 1, At, B1); PG8_BAR; PG8_SCHED;
	s_setprio 1
	s_waitcnt lgkmcnt(0)
	v_mfma_f32_16x16x32_bf16 v[94:97], v[34:37], v[172:175], v[94:97]
	v_mfma_f32_16x16x32_bf16 v[90:93], v[42:45], v[172:175], v[90:93]
	v_mfma_f32_16x16x32_bf16 v[78:81], v[34:37], v[220:223], v[78:81]
	v_mfma_f32_16x16x32_bf16 v[74:77], v[42:45], v[220:223], v[74:77]
	v_mfma_f32_16x16x32_bf16 v[30:33], v[34:37], v[228:231], v[30:33]
	v_mfma_f32_16x16x32_bf16 v[26:29], v[42:45], v[228:231], v[26:29]
	v_mfma_f32_16x16x32_bf16 v[14:17], v[34:37], v[246:249], v[14:17]
	v_mfma_f32_16x16x32_bf16 v[10:13], v[42:45], v[246:249], v[10:13]
	v_mfma_f32_16x16x32_bf16 v[94:97], v[38:41], v[182:185], v[94:97]
	v_mfma_f32_16x16x32_bf16 v[90:93], v[46:49], v[182:185], v[90:93]
	v_mfma_f32_16x16x32_bf16 v[78:81], v[38:41], v[224:227], v[78:81]
	v_mfma_f32_16x16x32_bf16 v[74:77], v[46:49], v[224:227], v[74:77]
	v_mfma_f32_16x16x32_bf16 v[30:33], v[38:41], v[242:245], v[30:33]
	v_mfma_f32_16x16x32_bf16 v[26:29], v[46:49], v[242:245], v[26:29]
	v_mfma_f32_16x16x32_bf16 v[14:17], v[38:41], v[250:253], v[14:17]
	v_mfma_f32_16x16x32_bf16 v[10:13], v[46:49], v[250:253], v[10:13]
	s_setprio 0
	s_setprio 1
	v_mfma_f32_16x16x32_bf16 v[22:25], v[50:53], v[228:231], v[22:25]
	v_mfma_f32_16x16x32_bf16 v[18:21], v[58:61], v[228:231], v[18:21]
	v_mfma_f32_16x16x32_bf16 v[6:9], v[50:53], v[246:249], v[6:9]
	v_mfma_f32_16x16x32_bf16 v[2:5], v[58:61], v[246:249], v[2:5]
	v_mfma_f32_16x16x32_bf16 v[34:37], v[50:53], v[172:175], v[86:89]
	v_mfma_f32_16x16x32_bf16 v[38:41], v[58:61], v[172:175], v[82:85]
	v_mfma_f32_16x16x32_bf16 v[42:45], v[50:53], v[220:223], v[70:73]
	v_mfma_f32_16x16x32_bf16 v[46:49], v[58:61], v[220:223], v[66:69]
	v_mfma_f32_16x16x32_bf16 v[22:25], v[54:57], v[242:245], v[22:25]
	v_mfma_f32_16x16x32_bf16 v[18:21], v[62:65], v[242:245], v[18:21]
	v_mfma_f32_16x16x32_bf16 v[6:9], v[54:57], v[250:253], v[6:9]
	v_mfma_f32_16x16x32_bf16 v[2:5], v[62:65], v[250:253], v[2:5]
	v_mfma_f32_16x16x32_bf16 v[34:37], v[54:57], v[182:185], v[34:37]
	v_mfma_f32_16x16x32_bf16 v[38:41], v[62:65], v[182:185], v[38:41]
	v_mfma_f32_16x16x32_bf16 v[42:45], v[54:57], v[224:227], v[42:45]
	v_mfma_f32_16x16x32_bf16 v[46:49], v[62:65], v[224:227], v[46:49]
	s_setprio 0
	s_barrier
	s_add_i32 s60, 0, 0x18000
	s_add_i32 s61, 0, 0x1c000
	v_add_u32_e32 v62, s60, v180
	v_add_u32_e32 v66, s61, v180
	ds_read_b128 v[50:53], v62
	ds_read_b128 v[54:57], v62 offset:1024
	ds_read_b128 v[58:61], v62 offset:2048
	ds_read_b128 v[62:65], v62 offset:3072
	ds_read_b128 v[172:175], v66
	ds_read_b128 v[182:185], v66 offset:1024
	ds_read_b128 v[220:223], v66 offset:2048
	ds_read_b128 v[224:227], v66 offset:3072
	s_add_u32 s42, s42, 0x40000
	s_addc_u32 s43, s43, 0
	s_mov_b32 m0, s53
	ds_read_b128 v[66:69], v181 offset:32768
	ds_read_b128 v[70:73], v181 offset:33792
	ds_read_b128 v[82:85], v181 offset:34816
	ds_read_b128 v[86:89], v181 offset:35840
	ds_read_b128 v[228:231], v181 offset:36864
	ds_read_b128 v[242:245], v181 offset:37888
	ds_read_b128 v[246:249], v181 offset:38912
	ds_read_b128 v[250:253], v181 offset:39936
	global_load_lds_dwordx4 v166, s[42:43]
	s_mov_b32 m0, s55
	s_nop 0
	global_load_lds_dwordx4 v164, s[42:43]
	s_waitcnt vmcnt(8)
	s_waitcnt lgkmcnt(0)
	s_barrier
	s_setprio 1
	s_waitcnt lgkmcnt(0)
	v_mfma_f32_16x16x32_bf16 v[158:161], v[50:53], v[66:69], v[158:161]
	v_mfma_f32_16x16x32_bf16 v[154:157], v[58:61], v[66:69], v[154:157]
	v_mfma_f32_16x16x32_bf16 v[142:145], v[50:53], v[82:85], v[142:145]
	v_mfma_f32_16x16x32_bf16 v[138:141], v[58:61], v[82:85], v[138:141]
	v_mfma_f32_16x16x32_bf16 v[126:129], v[50:53], v[228:231], v[126:129]
	v_mfma_f32_16x16x32_bf16 v[122:125], v[58:61], v[228:231], v[122:125]
	v_mfma_f32_16x16x32_bf16 v[110:113], v[50:53], v[246:249], v[110:113]
	v_mfma_f32_16x16x32_bf16 v[106:109], v[58:61], v[246:249], v[106:109]
	v_mfma_f32_16x16x32_bf16 v[158:161], v[54:57], v[70:73], v[158:161]
	v_mfma_f32_16x16x32_bf16 v[154:157], v[62:65], v[70:73], v[154:157]
	v_mfma_f32_16x16x32_bf16 v[142:145], v[54:57], v[86:89], v[142:145]
	v_mfma_f32_16x16x32_bf16 v[138:141], v[62:65], v[86:89], v[138:141]
	v_mfma_f32_16x16x32_bf16 v[126:129], v[54:57], v[242:245], v[126:129]
	v_mfma_f32_16x16x32_bf16 v[122:125], v[62:65], v[242:245], v[122:125]
	v_mfma_f32_16x16x32_bf16 v[110:113], v[54:57], v[250:253], v[110:113]
	v_mfma_f32_16x16x32_bf16 v[106:109], v[62:65], v[250:253], v[106:109]
	s_setprio 0
	s_setprio 1
	v_mfma_f32_16x16x32_bf16 v[150:153], v[172:175], v[66:69], v[150:153]
	v_mfma_f32_16x16x32_bf16 v[66:69], v[220:223], v[66:69], v[146:149]
	v_mfma_f32_16x16x32_bf16 v[146:149], v[224:227], v[70:73], v[66:69]
	v_mfma_f32_16x16x32_bf16 v[66:69], v[172:175], v[82:85], v[134:137]
	v_mfma_f32_16x16x32_bf16 v[134:137], v[182:185], v[86:89], v[66:69]
	v_mfma_f32_16x16x32_bf16 v[66:69], v[220:223], v[82:85], v[130:133]
	v_mfma_f32_16x16x32_bf16 v[130:133], v[224:227], v[86:89], v[66:69]
	v_mfma_f32_16x16x32_bf16 v[66:69], v[172:175], v[228:231], v[118:121]
	v_mfma_f32_16x16x32_bf16 v[118:121], v[182:185], v[242:245], v[66:69]
	v_mfma_f32_16x16x32_bf16 v[66:69], v[220:223], v[228:231], v[114:117]
	v_mfma_f32_16x16x32_bf16 v[114:117], v[224:227], v[242:245], v[66:69]
	v_mfma_f32_16x16x32_bf16 v[66:69], v[172:175], v[246:249], v[102:105]
	v_mfma_f32_16x16x32_bf16 v[102:105], v[182:185], v[250:253], v[66:69]
	v_mfma_f32_16x16x32_bf16 v[66:69], v[220:223], v[246:249], v[98:101]
	v_mfma_f32_16x16x32_bf16 v[150:153], v[182:185], v[70:73], v[150:153]
	v_mfma_f32_16x16x32_bf16 v[98:101], v[224:227], v[250:253], v[66:69]
	s_setprio 0
	s_barrier
; #define PG8_STAGE(bufoff, gbase, voff) do { _Pragma("unroll") for (int _i = 0; _i < 2; ++_i) \
;         __builtin_amdgcn_global_load_lds((const unsigned*)((const char*)(gbase) + (voff)[_i]), (PG8_LAS unsigned*)(lds + (bufoff) + ldsw + _i * 8192), 16, 0, 0); } while (0)
; #define PG8_LDA(dst, b, h) do { _Pragma("unroll") for (int m = 0; m < 4; ++m) _Pragma("unroll") for (int k = 0; k < 2; ++k) dst[m][k] = *(const PG8_LAS bf16x8*)(lds + PG8_SA(b, h) + aoff + m * 2048 + k * 1024); } while (0)
; #define PG8_MMA(ai, bj, At, Bt) do { __builtin_amdgcn_s_setprio(1); _Pragma("unroll") for (int m = 0; m < 4; ++m) _Pragma("unroll") for (int n = 0; n < 2; ++n) _Pragma("unroll") for (int k = 0; k < 2; ++k) \
;         acc[ai][bj][m][n] = __builtin_amdgcn_mfma_f32_16x16x32_bf16(Bt[n][k], At[m][k], acc[ai][bj][m][n], 0, 0, 0); __builtin_amdgcn_s_setprio(0); } while (0)
; #define PG8_WAIT_V(n) asm volatile("s_waitcnt vmcnt(" #n ")" ::: "memory")
; #define PG8_WAIT_L(n) asm volatile("s_waitcnt lgkmcnt(" #n ")" ::: "memory")
; #define PG8_BAR __builtin_amdgcn_s_barrier()
; #define PG8_SCHED __builtin_amdgcn_sched_barrier(0)
; template <class Epi, class Sched, bool ALIGN_EPI = false, bool SP2 = false>
; __device__ __forceinline__ void gemm_phase(PG8_LAS unsigned char* lds, const Gemm g, const Sched& S, const Epi& E, int wv) {
;     ...
;             PG8_LDA(At, 1, 1); PG8_STAGE(PG8_SB(1, 0), b3, voffB); PG8_STAGE(PG8_SB(1, 1), b3 + hstepB, voffB); PG8_STAGE(PG8_SA(1, 0), a3, voffA);
;             PG8_WAIT_V(8); PG8_WAIT_L(0); PG8_BAR; PG8_MMA(1, 0, At, B0); PG8_MMA(1, 1, At, B1); PG8_BAR; PG8_SCHED;
;     DI void operator()(const f32x4 (&acc)[2][2][4][2], const pg8::Unit& u, int wr, int wc, int fr, int fq) const {
;     ...
;         const int row0 = u.pm * 256 + wr * 64 + fr, col0 = u.pn * 128 + wc * 32 + 8 * fq, lane = fq * 16 + fr, cc = u.pn * 256 + wc * 32 + 8 * fq;
;         f32x4 c1[2][2], c2[2][2];
; #pragma unroll
;         for (int bj = 0; bj < 2; ++bj)
; #pragma unroll
;             for (int n = 0; n < 2; ++n) { c1[bj][n] = *(const f32x4*)(C1 + cc + bj * 128 + n * 4); c2[bj][n] = *(const f32x4*)(C2 + cc + bj * 128 + n * 4); }
; #pragma unroll
;         for (int ai = 0; ai < 2; ++ai)
; #pragma unroll
;             for (int m = 0; m < 4; ++m) { const int row = row0 + ai * 128 + m * 16; float mu, rstd; row_stats(STAT, row, fq, lane, mu, rstd);
	s_add_i32 s42, s60, s50
	v_lshl_add_u64 v[82:83], v[176:177], 0, s[62:63]
	s_mov_b32 m0, s42
	s_nop 0
	ds_read_b128 v[66:69], v181 offset:49152
	ds_read_b128 v[70:73], v181 offset:50176
	ds_read_b128 v[228:231], v181 offset:51200
	ds_read_b128 v[242:245], v181 offset:52224
	ds_read_b128 v[246:249], v181 offset:53248
	ds_read_b128 v[250:253], v181 offset:54272
	ds_read_b128 v[232:235], v181 offset:55296
	ds_read_b128 v[236:239], v181 offset:56320
	global_load_lds_dwordx4 v[82:83], off
	s_add_i32 m0, s42, 0x2000
	s_add_u32 s2, s2, 0x40080
	v_lshl_add_u64 v[82:83], v[186:187], 0, s[62:63]
	s_addc_u32 s3, s3, 0
	s_add_i32 s42, s61, s50
	global_load_lds_dwordx4 v[82:83], off
	s_mov_b32 m0, s42
	s_nop 0
	global_load_lds_dwordx4 v0, s[2:3]
	s_add_i32 m0, s42, 0x2000
	s_nop 0
	global_load_lds_dwordx4 v162, s[2:3]
	v_lshl_add_u64 v[82:83], v[196:197], 0, s[62:63]
	s_mov_b32 m0, s83
	s_nop 0
	global_load_lds_dwordx4 v[82:83], off
	v_lshl_add_u64 v[82:83], v[240:241], 0, s[62:63]
	s_mov_b32 m0, s87
	s_nop 0
	global_load_lds_dwordx4 v[82:83], off
	s_waitcnt vmcnt(8)
	s_waitcnt lgkmcnt(0)
	s_barrier
	s_setprio 1
	s_waitcnt lgkmcnt(0)
	v_mfma_f32_16x16x32_bf16 v[82:85], v[50:53], v[66:69], v[94:97]
	v_mfma_f32_16x16x32_bf16 v[94:97], v[54:57], v[70:73], v[82:85]
	v_mfma_f32_16x16x32_bf16 v[82:85], v[58:61], v[66:69], v[90:93]
	v_mfma_f32_16x16x32_bf16 v[78:81], v[50:53], v[228:231], v[78:81]
	v_mfma_f32_16x16x32_bf16 v[74:77], v[58:61], v[228:231], v[74:77]
	v_mfma_f32_16x16x32_bf16 v[30:33], v[50:53], v[246:249], v[30:33]
	v_mfma_f32_16x16x32_bf16 v[26:29], v[58:61], v[246:249], v[26:29]
	v_mfma_f32_16x16x32_bf16 v[14:17], v[50:53], v[232:235], v[14:17]
	v_mfma_f32_16x16x32_bf16 v[10:13], v[58:61], v[232:235], v[10:13]
	v_mfma_f32_16x16x32_bf16 v[90:93], v[62:65], v[70:73], v[82:85]
	v_mfma_f32_16x16x32_bf16 v[78:81], v[54:57], v[242:245], v[78:81]
	v_mfma_f32_16x16x32_bf16 v[74:77], v[62:65], v[242:245], v[74:77]
	v_mfma_f32_16x16x32_bf16 v[30:33], v[54:57], v[250:253], v[30:33]
	v_mfma_f32_16x16x32_bf16 v[26:29], v[62:65], v[250:253], v[26:29]
	v_mfma_f32_16x16x32_bf16 v[14:17], v[54:57], v[236:239], v[14:17]
	v_mfma_f32_16x16x32_bf16 v[10:13], v[62:65], v[236:239], v[10:13]
	s_setprio 0
	s_setprio 1
	v_mfma_f32_16x16x32_bf16 v[34:37], v[172:175], v[66:69], v[34:37]
	v_mfma_f32_16x16x32_bf16 v[86:89], v[182:185], v[70:73], v[34:37]
	v_mfma_f32_16x16x32_bf16 v[34:37], v[220:223], v[66:69], v[38:41]
	v_mfma_f32_16x16x32_bf16 v[82:85], v[224:227], v[70:73], v[34:37]
	v_mfma_f32_16x16x32_bf16 v[34:37], v[172:175], v[228:231], v[42:45]
	v_mfma_f32_16x16x32_bf16 v[70:73], v[182:185], v[242:245], v[34:37]
	v_mfma_f32_16x16x32_bf16 v[34:37], v[220:223], v[228:231], v[46:49]
	v_mfma_f32_16x16x32_bf16 v[22:25], v[172:175], v[246:249], v[22:25]
	v_mfma_f32_16x16x32_bf16 v[18:21], v[220:223], v[246:249], v[18:21]
	v_mfma_f32_16x16x32_bf16 v[6:9], v[172:175], v[232:235], v[6:9]
	v_mfma_f32_16x16x32_bf16 v[2:5], v[220:223], v[232:235], v[2:5]
	v_mfma_f32_16x16x32_bf16 v[66:69], v[224:227], v[242:245], v[34:37]
	v_mfma_f32_16x16x32_bf16 v[22:25], v[182:185], v[250:253], v[22:25]
	v_mfma_f32_16x16x32_bf16 v[18:21], v[224:227], v[250:253], v[18:21]
	v_mfma_f32_16x16x32_bf16 v[6:9], v[182:185], v[236:239], v[6:9]
	v_mfma_f32_16x16x32_bf16 v[2:5], v[224:227], v[236:239], v[2:5]
	s_setprio 0
	s_barrier
	s_add_i32 s96, s96, 2
	s_add_u32 s40, s40, 0x100
	s_addc_u32 s41, s41, 0
	s_add_u32 s94, s94, 0x100
	s_addc_u32 s95, s95, 0
	s_cmp_gt_u32 s96, 13
	s_cbranch_scc0 .LBB0_1893
	v_mov_b32_e32 v173, v178
	v_mov_b32_e32 v177, v179
	s_lshl_b32 s2, s34, 8
	s_add_i32 s2, s2, s58
	v_add_u32_e32 v172, s2, v173
	s_lshl_b32 s2, s15, 8
	v_lshlrev_b32_e32 v173, 2, v173
	v_lshlrev_b32_e32 v174, 3, v177
	s_or_b32 s2, s2, s82
	v_lshl_add_u32 v173, v177, 6, v173
	v_add_u32_e32 v34, s2, v174
	s_lshl_b32 s2, s15, 7
	v_xor_b32_e32 v183, 64, v173
	v_xor_b32_e32 v182, 0x80, v173
	v_ashrrev_i32_e32 v173, 31, v172
	v_ashrrev_i32_e32 v35, 31, v34
	s_or_b32 s2, s2, s82
	v_ashrrev_i32_e32 v175, 31, v174
	v_lshlrev_b64 v[184:185], 7, v[172:173]
	v_lshlrev_b64 v[34:35], 2, v[34:35]
	v_add_u32_e32 v176, s2, v174
	v_lshl_add_u64 v[184:185], s[22:23], 0, v[184:185]
	v_lshlrev_b64 v[174:175], 2, v[174:175]
	v_lshl_add_u64 v[36:37], s[24:25], 0, v[34:35]
	v_lshl_add_u64 v[50:51], s[26:27], 0, v[34:35]
	v_lshl_add_u64 v[196:197], v[184:185], 0, v[174:175]
	global_load_dwordx4 v[46:49], v[36:37], off offset:16
	global_load_dwordx4 v[62:65], v[36:37], off
	global_load_dwordx4 v[42:45], v[50:51], off offset:16
	global_load_dwordx4 v[58:61], v[50:51], off
	global_load_dwordx4 v[38:41], v[36:37], off offset:528
	global_load_dwordx4 v[54:57], v[36:37], off offset:512
	s_nop 0
	global_load_dwordx4 v[34:37], v[50:51], off offset:528
	s_nop 0
	global_load_dwordx4 v[50:53], v[50:51], off offset:512
	s_nop 0
	global_load_dwordx4 v[184:187], v[196:197], off offset:16
	global_load_dwordx4 v[220:223], v[196:197], off
	s_and_b64 vcc, exec, s[28:29]
	s_cbranch_vccz .LBB0_1896
	s_barrier
